# cross-attention K tile pitch 528 -> 544 bytes: the ds_read_b128 K fragment reads become bank-conflict free for the gfx950 lane groups (one 2-way conflict per group before)
# baseline (speedup 1.0000x reference)
.LBB0_2487:
	s_cmp_lt_i32 s86, 13
	s_cselect_b64 s[0:1], -1, 0
	s_and_b64 s[2:3], s[0:1], s[2:3]
	s_andn2_b64 vcc, exec, s[2:3]
	s_cbranch_vccnz .LBB0_2496
	s_cmpk_gt_i32 s90, 0x3ff
	s_cbranch_scc1 .LBB0_2496
	v_and_b32_e32 v1, 15, v153
	v_readlane_b32 s2, v251, 7
	v_mov_b32_e32 v139, 0
	v_lshlrev_b32_e32 v9, 4, v153
	v_lshl_or_b32 v137, s2, 4, v1
	v_and_b32_e32 v140, 0x70, v9
	v_mov_b32_e32 v141, v139
	v_mul_u32_u24_e32 v204, 0x90, v1
	v_mul_u32_u24_e32 v213, 0x220, v1
	v_or_b32_e32 v1, 48, v152
	v_lshl_add_u64 v[2:3], s[96:97], 0, v[140:141]
	s_mov_b64 s[4:5], 0x1d200000
	v_mul_u32_u24_e32 v214, 0x220, v1
	v_mul_u32_u24_e32 v215, 0x90, v1
	v_or_b32_e32 v1, 0x70, v152
	v_lshlrev_b32_e32 v7, 5, v153
	v_lshl_add_u64 v[142:143], v[2:3], 0, s[4:5]
	s_mov_b32 s4, 0xfc00
	s_mov_b32 s5, 0xff00
	v_mov_b32_e32 v12, 0x8000
	v_mul_u32_u24_e32 v216, 0x90, v1
	v_or_b32_e32 v1, 0xb0, v152
	v_lshrrev_b32_e32 v5, 4, v152
	v_and_b32_e32 v2, 0x7c00, v7
	v_and_b32_e32 v4, 0x7f00, v7
	v_add_u32_e32 v3, 0x4000, v7
	v_or_b32_e32 v11, 0x8000, v7
	v_bitop3_b32 v10, v7, s4, v12 bitop3:0xc8
	v_bitop3_b32 v12, v7, s5, v12 bitop3:0xc8
	v_add_u32_e32 v7, 0xc000, v7
	v_mul_u32_u24_e32 v217, 0x90, v1
	v_or_b32_e32 v1, 0xf0, v152
	v_lshlrev_b32_e32 v136, 3, v5
	v_mul_u32_u24_e32 v218, 0x90, v1
	v_lshlrev_b32_e32 v18, 2, v5
	v_lshlrev_b32_e32 v1, 1, v7
	v_and_b32_e32 v5, 7, v153
	v_and_b32_e32 v1, 0x3fe00, v1
	v_lshlrev_b32_e32 v5, 4, v5
	s_mov_b32 s6, 0x1d200080
	v_or3_b32 v144, v1, v5, s6
	v_lshlrev_b32_e32 v1, 1, v11
	v_add_u32_e32 v15, 0x200, v153
	v_and_b32_e32 v1, 0x1fe00, v1
	v_lshrrev_b32_e32 v17, 5, v15
	v_lshrrev_b32_e32 v15, 3, v15
	v_or3_b32 v146, v1, v5, s6
	v_lshlrev_b32_e32 v1, 1, v3
	v_lshrrev_b32_e32 v13, 3, v153
	v_mul_u32_u24_e32 v208, 0x90, v15
	v_or_b32_e32 v15, 0x400, v153
	v_and_b32_e32 v1, 0x1fe00, v1
	s_add_u32 s2, s96, 0xb000000
	v_and_b32_e32 v6, 0xfc00, v3
	v_and_b32_e32 v8, 0xff00, v3
	v_lshrrev_b32_e32 v19, 5, v15
	v_or3_b32 v148, v1, v5, s6
	v_lshlrev_b32_e32 v1, 9, v13
	v_and_b32_e32 v3, 31, v153
	s_addc_u32 s3, s97, 0
	v_lshrrev_b32_e32 v15, 3, v15
	v_or3_b32 v150, v1, v5, s6
	v_lshlrev_b32_e32 v1, 11, v19
	v_lshlrev_b32_e32 v3, 4, v3
	s_mov_b32 s6, 0x1ca20000
	s_add_u32 s9, s96, 0x1ca00000
	v_and_b32_e32 v141, 0x1f0, v9
	v_lshrrev_b32_e32 v9, 5, v153
	v_mul_u32_u24_e32 v210, 0x90, v15
	v_add_u32_e32 v15, 0x600, v153
	v_or3_b32 v154, v1, v3, s6
	v_lshlrev_b32_e32 v1, 11, v17
	s_addc_u32 s16, s97, 0
	v_lshlrev_b32_e32 v0, 3, v153
	v_lshrrev_b32_e32 v20, 5, v15
	v_or3_b32 v156, v1, v3, s6
	v_lshlrev_b32_e32 v1, 11, v9
	v_and_b32_e32 v0, 0xf8, v0
	v_and_b32_e32 v14, 0x1fc00, v7
	v_and_b32_e32 v16, 0x1ff00, v7
	v_lshrrev_b32_e32 v15, 3, v15
	s_add_u32 s4, s96, 0x3000000
	v_or3_b32 v158, v1, v3, s6
	v_lshl_or_b32 v138, v20, 11, v3
	s_mov_b64 s[6:7], 0x1ca20000
	v_and_b32_e32 v203, 48, v153
	v_mul_u32_u24_e32 v205, 0x220, v9
	v_mul_u32_u24_e32 v206, 0x90, v13
	v_mul_u32_u24_e32 v207, 0x220, v17
	v_mul_u32_u24_e32 v209, 0x220, v19
	v_mul_u32_u24_e32 v211, 0x220, v20
	v_mul_u32_u24_e32 v212, 0x90, v15
	s_addc_u32 s5, s97, 0
	v_mov_b32_e32 v145, v139
	v_mov_b32_e32 v147, v139
	v_mov_b32_e32 v149, v139
	v_mov_b32_e32 v151, v139
	v_mov_b32_e32 v155, v139
	v_mov_b32_e32 v157, v139
	v_mov_b32_e32 v159, v139
	v_lshl_add_u64 v[160:161], v[138:139], 0, s[6:7]
	s_mov_b32 s7, 0
	v_lshlrev_b32_e32 v162, 1, v136
	v_lshlrev_b32_e32 v164, 1, v0
	v_lshlrev_b32_e32 v166, 1, v2
	v_lshlrev_b32_e32 v168, 1, v4
	v_lshlrev_b32_e32 v170, 1, v6
	v_lshlrev_b32_e32 v172, 1, v8
	v_lshlrev_b32_e32 v174, 1, v10
	v_lshlrev_b32_e32 v176, 1, v12
	v_lshlrev_b32_e32 v178, 1, v14
	v_lshlrev_b32_e32 v180, 1, v16
	s_mov_b32 s8, 0x3d800000
	s_mov_b32 s17, 0xf149f2ca
	s_mov_b64 s[10:11], 0x80
	s_mov_b64 s[12:13], 0x20000
	v_lshlrev_b32_e32 v182, 1, v18
	s_mov_b32 s18, s90
	s_branch .LBB0_2491

.LBB0_2492:
	s_and_b64 s[20:21], s[14:15], exec
	s_cselect_b32 s20, 0x11800, 0
	s_add_i32 s20, s20, 0
	v_add_u32_e32 v129, s20, v141
	v_add_u32_e32 v130, s20, v140
	v_add_u32_e32 v131, v129, v205
	s_waitcnt vmcnt(7)
	ds_write_b128 v131, v[60:63]
	v_add_u32_e32 v131, v130, v206
	s_waitcnt vmcnt(6)
	ds_write_b128 v131, v[64:67] offset:34816
	v_add_u32_e32 v131, v129, v207
	s_waitcnt vmcnt(5)
	ds_write_b128 v131, v[72:75]
	v_add_u32_e32 v131, v130, v208
	s_waitcnt vmcnt(4)
	ds_write_b128 v131, v[80:83] offset:34816
	v_add_u32_e32 v131, v129, v209
	s_waitcnt vmcnt(3)
	ds_write_b128 v131, v[84:87]
	v_add_u32_e32 v131, v130, v210
	v_add_u32_e32 v129, v129, v211
	s_waitcnt vmcnt(2)
	ds_write_b128 v131, v[88:91] offset:34816
	s_waitcnt vmcnt(1)
	ds_write_b128 v129, v[100:103]
	v_add_u32_e32 v129, v130, v212
	s_cmp_eq_u32 s6, 1
	s_waitcnt vmcnt(0)
	ds_write_b128 v129, v[104:107] offset:34816
	s_waitcnt lgkmcnt(0)
	s_barrier
	s_cbranch_scc1 .LBB0_2494
	v_lshl_add_u64 v[60:61], s[96:97], 0, v[198:199]
	v_lshl_add_u64 v[64:65], s[96:97], 0, v[192:193]
	v_lshl_add_u64 v[72:73], s[96:97], 0, v[196:197]
	v_lshl_add_u64 v[80:81], s[96:97], 0, v[190:191]
	v_lshl_add_u64 v[84:85], s[96:97], 0, v[194:195]
	v_lshl_add_u64 v[88:89], s[96:97], 0, v[188:189]
	v_lshl_add_u64 v[100:101], s[96:97], 0, v[200:201]
	v_lshl_add_u64 v[104:105], s[96:97], 0, v[186:187]
	global_load_dwordx4 v[60:63], v[60:61], off
	s_nop 0
	global_load_dwordx4 v[64:67], v[64:65], off
	s_nop 0
	global_load_dwordx4 v[72:75], v[72:73], off
	s_nop 0
	global_load_dwordx4 v[80:83], v[80:81], off
	s_nop 0
	global_load_dwordx4 v[84:87], v[84:85], off
	s_nop 0
	global_load_dwordx4 v[88:91], v[88:89], off
	s_nop 0
	global_load_dwordx4 v[100:103], v[100:101], off
	s_nop 0
	global_load_dwordx4 v[104:107], v[104:105], off
.LBB0_2494:
	v_add3_u32 v244, s20, v203, v213
	v_add3_u32 v245, s20, v203, v214
	v_add3_u32 v219, s20, v136, v204
	v_mov_b32_e32 v175, v128
	s_xor_b64 s[14:15], s[14:15], -1
	s_add_i32 s6, s6, -1
	ds_read_b128 v[220:223], v244 offset:0
	ds_read_b128 v[224:227], v244 offset:64
	ds_read_b128 v[228:231], v244 offset:128
	ds_read_b128 v[232:235], v244 offset:192
	v_add_u32_e32 v219, 0x8800, v219
	s_waitcnt lgkmcnt(3)
	v_mfma_f32_16x16x32_bf16 v[236:239], v[220:223], v[20:23], 0
	ds_read_b128 v[220:223], v244 offset:256
	s_waitcnt lgkmcnt(3)
	v_mfma_f32_16x16x32_bf16 v[236:239], v[224:227], v[24:27], v[236:239]
	ds_read_b128 v[224:227], v244 offset:320
	v_lshl_add_u64 v[186:187], v[186:187], 0, s[10:11]
	s_waitcnt lgkmcnt(3)
	v_mfma_f32_16x16x32_bf16 v[236:239], v[228:231], v[28:31], v[236:239]
	ds_read_b128 v[228:231], v244 offset:384
	s_waitcnt lgkmcnt(3)
	v_mfma_f32_16x16x32_bf16 v[236:239], v[232:235], v[32:35], v[236:239]
	ds_read_b128 v[232:235], v244 offset:448
	v_lshl_add_u64 v[188:189], v[188:189], 0, s[10:11]
	s_waitcnt lgkmcnt(3)
	v_mfma_f32_16x16x32_bf16 v[236:239], v[220:223], v[36:39], v[236:239]
	ds_read_b128 v[220:223], v244 offset:8704
	s_waitcnt lgkmcnt(3)
	v_mfma_f32_16x16x32_bf16 v[236:239], v[224:227], v[44:47], v[236:239]
	ds_read_b128 v[224:227], v244 offset:8768
	v_lshl_add_u64 v[190:191], v[190:191], 0, s[10:11]
	s_waitcnt lgkmcnt(3)
	v_mfma_f32_16x16x32_bf16 v[236:239], v[228:231], v[48:51], v[236:239]
	ds_read_b128 v[228:231], v244 offset:8832
	s_waitcnt lgkmcnt(3)
	v_mfma_f32_16x16x32_bf16 v[236:239], v[232:235], v[52:55], v[236:239]
	ds_read_b128 v[232:235], v244 offset:8896
	v_lshl_add_u64 v[192:193], v[192:193], 0, s[10:11]
	s_waitcnt lgkmcnt(3)
	v_mfma_f32_16x16x32_bf16 v[240:243], v[220:223], v[20:23], 0
	ds_read_b128 v[220:223], v244 offset:8960
	s_waitcnt lgkmcnt(3)
	v_mfma_f32_16x16x32_bf16 v[240:243], v[224:227], v[24:27], v[240:243]
	ds_read_b128 v[224:227], v244 offset:9024
	v_lshl_add_u64 v[194:195], v[194:195], 0, s[12:13]
	s_waitcnt lgkmcnt(3)
	v_mfma_f32_16x16x32_bf16 v[240:243], v[228:231], v[28:31], v[240:243]
	ds_read_b128 v[228:231], v244 offset:9088
	s_waitcnt lgkmcnt(3)
	v_mfma_f32_16x16x32_bf16 v[240:243], v[232:235], v[32:35], v[240:243]
	ds_read_b128 v[232:235], v244 offset:9152
	v_lshl_add_u64 v[196:197], v[196:197], 0, s[12:13]
	s_waitcnt lgkmcnt(3)
	v_mfma_f32_16x16x32_bf16 v[240:243], v[220:223], v[36:39], v[240:243]
	ds_read_b128 v[220:223], v244 offset:17408
	v_pk_mul_f32 v[236:237], v[236:237], s[8:9] op_sel_hi:[1,0]
	v_pk_mul_f32 v[238:239], v[238:239], s[8:9] op_sel_hi:[1,0]
	s_waitcnt lgkmcnt(3)
	v_mfma_f32_16x16x32_bf16 v[240:243], v[224:227], v[44:47], v[240:243]
	ds_read_b128 v[224:227], v244 offset:17472
	v_lshl_add_u64 v[198:199], v[198:199], 0, s[12:13]
	s_waitcnt lgkmcnt(3)
	v_mfma_f32_16x16x32_bf16 v[240:243], v[228:231], v[48:51], v[240:243]
	ds_read_b128 v[228:231], v244 offset:17536
	s_waitcnt lgkmcnt(3)
	v_mfma_f32_16x16x32_bf16 v[240:243], v[232:235], v[52:55], v[240:243]
	ds_read_b128 v[232:235], v244 offset:17600
	v_lshl_add_u64 v[200:201], v[200:201], 0, s[12:13]
	s_waitcnt lgkmcnt(3)
	v_mfma_f32_16x16x32_bf16 v[128:131], v[220:223], v[20:23], 0
	ds_read_b128 v[220:223], v244 offset:17664
	s_waitcnt lgkmcnt(3)
	v_mfma_f32_16x16x32_bf16 v[128:131], v[224:227], v[24:27], v[128:131]
	ds_read_b128 v[224:227], v244 offset:17728
	s_waitcnt lgkmcnt(3)
	v_mfma_f32_16x16x32_bf16 v[128:131], v[228:231], v[28:31], v[128:131]
	ds_read_b128 v[228:231], v244 offset:17792
	s_waitcnt lgkmcnt(3)
	v_mfma_f32_16x16x32_bf16 v[128:131], v[232:235], v[32:35], v[128:131]
	ds_read_b128 v[232:235], v244 offset:17856
	s_waitcnt lgkmcnt(3)
	v_mfma_f32_16x16x32_bf16 v[128:131], v[220:223], v[36:39], v[128:131]
	ds_read_b128 v[220:223], v245 offset:0
	v_pk_mul_f32 v[240:241], v[240:241], s[8:9] op_sel_hi:[1,0]
	v_pk_mul_f32 v[242:243], v[242:243], s[8:9] op_sel_hi:[1,0]
	s_waitcnt lgkmcnt(3)
	v_mfma_f32_16x16x32_bf16 v[128:131], v[224:227], v[44:47], v[128:131]
	ds_read_b128 v[224:227], v245 offset:64
	s_waitcnt lgkmcnt(3)
	v_mfma_f32_16x16x32_bf16 v[128:131], v[228:231], v[48:51], v[128:131]
	ds_read_b128 v[228:231], v245 offset:128
	s_waitcnt lgkmcnt(3)
	v_mfma_f32_16x16x32_bf16 v[128:131], v[232:235], v[52:55], v[128:131]
	ds_read_b128 v[232:235], v245 offset:192
	s_waitcnt lgkmcnt(3)
	v_mfma_f32_16x16x32_bf16 v[132:135], v[220:223], v[20:23], 0
	ds_read_b128 v[220:223], v245 offset:256
	s_waitcnt lgkmcnt(3)
	v_mfma_f32_16x16x32_bf16 v[132:135], v[224:227], v[24:27], v[132:135]
	ds_read_b128 v[224:227], v245 offset:320
	s_waitcnt lgkmcnt(3)
	v_mfma_f32_16x16x32_bf16 v[132:135], v[228:231], v[28:31], v[132:135]
	ds_read_b128 v[228:231], v245 offset:384
	s_waitcnt lgkmcnt(3)
	v_mfma_f32_16x16x32_bf16 v[132:135], v[232:235], v[32:35], v[132:135]
	ds_read_b128 v[232:235], v245 offset:448
	s_waitcnt lgkmcnt(3)
	v_mfma_f32_16x16x32_bf16 v[132:135], v[220:223], v[36:39], v[132:135]
	v_pk_mul_f32 v[128:129], v[128:129], s[8:9] op_sel_hi:[1,0]
	v_pk_mul_f32 v[130:131], v[130:131], s[8:9] op_sel_hi:[1,0]
	s_waitcnt lgkmcnt(2)
	v_mfma_f32_16x16x32_bf16 v[132:135], v[224:227], v[44:47], v[132:135]
	s_waitcnt lgkmcnt(1)
	v_mfma_f32_16x16x32_bf16 v[132:135], v[228:231], v[48:51], v[132:135]
	s_waitcnt lgkmcnt(0)
	v_mfma_f32_16x16x32_bf16 v[132:135], v[232:235], v[52:55], v[132:135]
	ds_read_b64 v[228:229], v219 offset:0
	ds_read_b64 v[230:231], v219 offset:32
	ds_read_b64 v[232:233], v219 offset:64
	ds_read_b64 v[234:235], v219 offset:96
	s_nop 3
	v_pk_mul_f32 v[132:133], v[132:133], s[8:9] op_sel_hi:[1,0]
	v_pk_mul_f32 v[134:135], v[134:135], s[8:9] op_sel_hi:[1,0]
	v_max3_f32 v167, v236, v237, v238
	v_max3_f32 v167, v167, v239, v240
	v_max3_f32 v167, v167, v241, v242
	v_max3_f32 v167, v167, v243, v128
	v_max3_f32 v167, v167, v129, v130
	v_max3_f32 v167, v167, v131, v132
	v_max3_f32 v167, v167, v133, v134
	v_max3_f32 v167, v167, s17, v135
	v_mov_b32_e32 v169, v167
	s_nop 1
	v_permlane16_swap_b32_e32 v167, v169
	v_max_f32_e32 v169, v169, v169
	v_max_f32_e32 v167, v167, v167
	v_max_f32_e32 v167, v167, v169
	v_mov_b32_e32 v169, v167
	s_nop 1
	v_permlane32_swap_b32_e32 v167, v169
	v_max3_f32 v165, v175, v167, v169
	v_sub_f32_e32 v173, v175, v165
	v_mul_f32_e32 v173, 0x3fb8aa3b, v173
	v_exp_f32_e32 v138, v173
	v_sub_f32_e32 v236, v236, v165
	v_sub_f32_e32 v237, v237, v165
	v_sub_f32_e32 v238, v238, v165
	v_sub_f32_e32 v239, v239, v165
	v_sub_f32_e32 v240, v240, v165
	v_sub_f32_e32 v241, v241, v165
	v_sub_f32_e32 v242, v242, v165
	v_sub_f32_e32 v243, v243, v165
	v_sub_f32_e32 v128, v128, v165
	v_sub_f32_e32 v129, v129, v165
	v_sub_f32_e32 v130, v130, v165
	v_sub_f32_e32 v131, v131, v165
	v_sub_f32_e32 v132, v132, v165
	v_sub_f32_e32 v133, v133, v165
	v_sub_f32_e32 v134, v134, v165
	v_sub_f32_e32 v135, v135, v165
	v_mul_f32_e32 v236, 0x3fb8aa3b, v236
	v_mul_f32_e32 v237, 0x3fb8aa3b, v237
	v_mul_f32_e32 v238, 0x3fb8aa3b, v238
	v_mul_f32_e32 v239, 0x3fb8aa3b, v239
	v_mul_f32_e32 v240, 0x3fb8aa3b, v240
	v_mul_f32_e32 v241, 0x3fb8aa3b, v241
	v_mul_f32_e32 v242, 0x3fb8aa3b, v242
	v_mul_f32_e32 v243, 0x3fb8aa3b, v243
	v_mul_f32_e32 v128, 0x3fb8aa3b, v128
	v_mul_f32_e32 v129, 0x3fb8aa3b, v129
	v_mul_f32_e32 v130, 0x3fb8aa3b, v130
	v_mul_f32_e32 v131, 0x3fb8aa3b, v131
	v_mul_f32_e32 v132, 0x3fb8aa3b, v132
	v_mul_f32_e32 v133, 0x3fb8aa3b, v133
	v_mul_f32_e32 v134, 0x3fb8aa3b, v134
	v_mul_f32_e32 v135, 0x3fb8aa3b, v135
	v_exp_f32_e32 v236, v236
	v_exp_f32_e32 v237, v237
	v_exp_f32_e32 v238, v238
	v_exp_f32_e32 v239, v239
	v_exp_f32_e32 v240, v240
	v_exp_f32_e32 v241, v241
	v_exp_f32_e32 v242, v242
	v_exp_f32_e32 v243, v243
	v_exp_f32_e32 v128, v128
	v_exp_f32_e32 v129, v129
	v_exp_f32_e32 v130, v130
	v_exp_f32_e32 v131, v131
	v_exp_f32_e32 v132, v132
	v_exp_f32_e32 v133, v133
	v_exp_f32_e32 v134, v134
	v_exp_f32_e32 v135, v135
	v_pk_mul_f32 v[124:125], v[124:125], v[138:139] op_sel_hi:[1,0]
	v_pk_mul_f32 v[126:127], v[126:127], v[138:139] op_sel_hi:[1,0]
	v_pk_mul_f32 v[120:121], v[120:121], v[138:139] op_sel_hi:[1,0]
	v_pk_mul_f32 v[122:123], v[122:123], v[138:139] op_sel_hi:[1,0]
	v_pk_mul_f32 v[116:117], v[116:117], v[138:139] op_sel_hi:[1,0]
	v_pk_mul_f32 v[118:119], v[118:119], v[138:139] op_sel_hi:[1,0]
	v_pk_mul_f32 v[112:113], v[112:113], v[138:139] op_sel_hi:[1,0]
	v_pk_mul_f32 v[114:115], v[114:115], v[138:139] op_sel_hi:[1,0]
	v_pk_mul_f32 v[108:109], v[108:109], v[138:139] op_sel_hi:[1,0]
	v_pk_mul_f32 v[110:111], v[110:111], v[138:139] op_sel_hi:[1,0]
	v_pk_mul_f32 v[96:97], v[96:97], v[138:139] op_sel_hi:[1,0]
	v_pk_mul_f32 v[98:99], v[98:99], v[138:139] op_sel_hi:[1,0]
	v_pk_mul_f32 v[92:93], v[92:93], v[138:139] op_sel_hi:[1,0]
	v_pk_mul_f32 v[94:95], v[94:95], v[138:139] op_sel_hi:[1,0]
	v_pk_mul_f32 v[76:77], v[76:77], v[138:139] op_sel_hi:[1,0]
	v_pk_mul_f32 v[78:79], v[78:79], v[138:139] op_sel_hi:[1,0]
	v_pk_mul_f32 v[68:69], v[68:69], v[138:139] op_sel_hi:[1,0]
	v_pk_mul_f32 v[70:71], v[70:71], v[138:139] op_sel_hi:[1,0]
	v_pk_mul_f32 v[56:57], v[56:57], v[138:139] op_sel_hi:[1,0]
	v_pk_mul_f32 v[58:59], v[58:59], v[138:139] op_sel_hi:[1,0]
	v_pk_mul_f32 v[40:41], v[40:41], v[138:139] op_sel_hi:[1,0]
	v_pk_mul_f32 v[42:43], v[42:43], v[138:139] op_sel_hi:[1,0]
	v_pk_mul_f32 v[16:17], v[16:17], v[138:139] op_sel_hi:[1,0]
	v_pk_mul_f32 v[18:19], v[18:19], v[138:139] op_sel_hi:[1,0]
	v_pk_mul_f32 v[12:13], v[12:13], v[138:139] op_sel_hi:[1,0]
	v_pk_mul_f32 v[14:15], v[14:15], v[138:139] op_sel_hi:[1,0]
	v_pk_mul_f32 v[8:9], v[8:9], v[138:139] op_sel_hi:[1,0]
	v_pk_mul_f32 v[10:11], v[10:11], v[138:139] op_sel_hi:[1,0]
	v_pk_mul_f32 v[4:5], v[4:5], v[138:139] op_sel_hi:[1,0]
	v_pk_mul_f32 v[6:7], v[6:7], v[138:139] op_sel_hi:[1,0]
	v_pk_mul_f32 v[0:1], v[0:1], v[138:139] op_sel_hi:[1,0]
	v_pk_mul_f32 v[2:3], v[2:3], v[138:139] op_sel_hi:[1,0]
	v_add_f32_e32 v171, 0, v236
	v_add_f32_e32 v171, v237, v171
	v_add_f32_e32 v171, v238, v171
	v_add_f32_e32 v171, v239, v171
	v_add_f32_e32 v171, v240, v171
	v_add_f32_e32 v171, v241, v171
	v_add_f32_e32 v171, v242, v171
	v_add_f32_e32 v171, v243, v171
	v_add_f32_e32 v171, v128, v171
	v_add_f32_e32 v171, v129, v171
	v_add_f32_e32 v171, v130, v171
	v_add_f32_e32 v171, v131, v171
	v_add_f32_e32 v171, v132, v171
	v_add_f32_e32 v171, v133, v171
	v_add_f32_e32 v171, v134, v171
	v_add_f32_e32 v171, v135, v171
	v_cvt_pk_bf16_f32 v220, v236, v237
	v_cvt_pk_bf16_f32 v221, v238, v239
	v_cvt_pk_bf16_f32 v222, v240, v241
	v_cvt_pk_bf16_f32 v223, v242, v243
	v_cvt_pk_bf16_f32 v224, v128, v129
	v_cvt_pk_bf16_f32 v225, v130, v131
	v_cvt_pk_bf16_f32 v226, v132, v133
	v_cvt_pk_bf16_f32 v227, v134, v135
	v_fmac_f32_e32 v171, v163, v138
	ds_read_b64 v[236:237], v219 offset:2304
	ds_read_b64 v[238:239], v219 offset:2336
	ds_read_b64 v[240:241], v219 offset:2368
	ds_read_b64 v[242:243], v219 offset:2400
	ds_read_b64 v[128:129], v219 offset:4608
	ds_read_b64 v[130:131], v219 offset:4640
	ds_read_b64 v[132:133], v219 offset:4672
	ds_read_b64 v[134:135], v219 offset:4704
	s_waitcnt lgkmcnt(10)
	s_nop 0
	v_mfma_f32_16x16x32_bf16 v[124:127], v[228:231], v[220:223], v[124:127]
	ds_read_b64 v[228:229], v219 offset:6912
	ds_read_b64 v[230:231], v219 offset:6944
	s_waitcnt lgkmcnt(10)
	v_mfma_f32_16x16x32_bf16 v[124:127], v[232:235], v[224:227], v[124:127]
	ds_read_b64 v[232:233], v219 offset:6976
	ds_read_b64 v[234:235], v219 offset:7008
	s_waitcnt lgkmcnt(10)
	v_mfma_f32_16x16x32_bf16 v[120:123], v[236:239], v[220:223], v[120:123]
	ds_read_b64 v[236:237], v219 offset:9216
	ds_read_b64 v[238:239], v219 offset:9248
	s_waitcnt lgkmcnt(10)
	v_mfma_f32_16x16x32_bf16 v[120:123], v[240:243], v[224:227], v[120:123]
	ds_read_b64 v[240:241], v219 offset:9280
	ds_read_b64 v[242:243], v219 offset:9312
	s_waitcnt lgkmcnt(10)
	v_mfma_f32_16x16x32_bf16 v[116:119], v[128:131], v[220:223], v[116:119]
	ds_read_b64 v[128:129], v219 offset:11520
	ds_read_b64 v[130:131], v219 offset:11552
	s_waitcnt lgkmcnt(10)
	v_mfma_f32_16x16x32_bf16 v[116:119], v[132:135], v[224:227], v[116:119]
	ds_read_b64 v[132:133], v219 offset:11584
	ds_read_b64 v[134:135], v219 offset:11616
	s_waitcnt lgkmcnt(10)
	v_mfma_f32_16x16x32_bf16 v[112:115], v[228:231], v[220:223], v[112:115]
	ds_read_b64 v[228:229], v219 offset:13824
	ds_read_b64 v[230:231], v219 offset:13856
	s_waitcnt lgkmcnt(10)
	v_mfma_f32_16x16x32_bf16 v[112:115], v[232:235], v[224:227], v[112:115]
	ds_read_b64 v[232:233], v219 offset:13888
	ds_read_b64 v[234:235], v219 offset:13920
	s_waitcnt lgkmcnt(10)
	v_mfma_f32_16x16x32_bf16 v[108:111], v[236:239], v[220:223], v[108:111]
	ds_read_b64 v[236:237], v219 offset:16128
	ds_read_b64 v[238:239], v219 offset:16160
	s_waitcnt lgkmcnt(10)
	v_mfma_f32_16x16x32_bf16 v[108:111], v[240:243], v[224:227], v[108:111]
	ds_read_b64 v[240:241], v219 offset:16192
	ds_read_b64 v[242:243], v219 offset:16224
	s_waitcnt lgkmcnt(10)
	v_mfma_f32_16x16x32_bf16 v[96:99], v[128:131], v[220:223], v[96:99]
	ds_read_b64 v[128:129], v219 offset:18432
	ds_read_b64 v[130:131], v219 offset:18464
	s_waitcnt lgkmcnt(10)
	v_mfma_f32_16x16x32_bf16 v[96:99], v[132:135], v[224:227], v[96:99]
	ds_read_b64 v[132:133], v219 offset:18496
	ds_read_b64 v[134:135], v219 offset:18528
	s_waitcnt lgkmcnt(10)
	v_mfma_f32_16x16x32_bf16 v[92:95], v[228:231], v[220:223], v[92:95]
	ds_read_b64 v[228:229], v219 offset:20736
	ds_read_b64 v[230:231], v219 offset:20768
	s_waitcnt lgkmcnt(10)
	v_mfma_f32_16x16x32_bf16 v[92:95], v[232:235], v[224:227], v[92:95]
	ds_read_b64 v[232:233], v219 offset:20800
	ds_read_b64 v[234:235], v219 offset:20832
	s_waitcnt lgkmcnt(10)
	v_mfma_f32_16x16x32_bf16 v[76:79], v[236:239], v[220:223], v[76:79]
	ds_read_b64 v[236:237], v219 offset:23040
	ds_read_b64 v[238:239], v219 offset:23072
	s_waitcnt lgkmcnt(10)
	v_mfma_f32_16x16x32_bf16 v[76:79], v[240:243], v[224:227], v[76:79]
	ds_read_b64 v[240:241], v219 offset:23104
	ds_read_b64 v[242:243], v219 offset:23136
	s_waitcnt lgkmcnt(10)
	v_mfma_f32_16x16x32_bf16 v[68:71], v[128:131], v[220:223], v[68:71]
	ds_read_b64 v[128:129], v219 offset:25344
	ds_read_b64 v[130:131], v219 offset:25376
	s_waitcnt lgkmcnt(10)
	v_mfma_f32_16x16x32_bf16 v[68:71], v[132:135], v[224:227], v[68:71]
	ds_read_b64 v[132:133], v219 offset:25408
	ds_read_b64 v[134:135], v219 offset:25440
	s_waitcnt lgkmcnt(10)
	v_mfma_f32_16x16x32_bf16 v[56:59], v[228:231], v[220:223], v[56:59]
	ds_read_b64 v[228:229], v219 offset:27648
	ds_read_b64 v[230:231], v219 offset:27680
	s_waitcnt lgkmcnt(10)
	v_mfma_f32_16x16x32_bf16 v[56:59], v[232:235], v[224:227], v[56:59]
	ds_read_b64 v[232:233], v219 offset:27712
	ds_read_b64 v[234:235], v219 offset:27744
	s_waitcnt lgkmcnt(10)
	v_mfma_f32_16x16x32_bf16 v[40:43], v[236:239], v[220:223], v[40:43]
	ds_read_b64 v[236:237], v219 offset:29952
	ds_read_b64 v[238:239], v219 offset:29984
	s_waitcnt lgkmcnt(10)
	v_mfma_f32_16x16x32_bf16 v[40:43], v[240:243], v[224:227], v[40:43]
	ds_read_b64 v[240:241], v219 offset:30016
	ds_read_b64 v[242:243], v219 offset:30048
	s_waitcnt lgkmcnt(10)
	v_mfma_f32_16x16x32_bf16 v[16:19], v[128:131], v[220:223], v[16:19]
	ds_read_b64 v[128:129], v219 offset:32256
	ds_read_b64 v[130:131], v219 offset:32288
	s_waitcnt lgkmcnt(10)
	v_mfma_f32_16x16x32_bf16 v[16:19], v[132:135], v[224:227], v[16:19]
	ds_read_b64 v[132:133], v219 offset:32320
	ds_read_b64 v[134:135], v219 offset:32352
	s_waitcnt lgkmcnt(10)
	v_mfma_f32_16x16x32_bf16 v[12:15], v[228:231], v[220:223], v[12:15]
	ds_read_b64 v[228:229], v219 offset:34560
	ds_read_b64 v[230:231], v219 offset:34592
	s_waitcnt lgkmcnt(10)
	v_mfma_f32_16x16x32_bf16 v[12:15], v[232:235], v[224:227], v[12:15]
	ds_read_b64 v[232:233], v219 offset:34624
	ds_read_b64 v[234:235], v219 offset:34656
	s_waitcnt lgkmcnt(10)
	v_mfma_f32_16x16x32_bf16 v[8:11], v[236:239], v[220:223], v[8:11]
	s_waitcnt lgkmcnt(8)
	v_mfma_f32_16x16x32_bf16 v[8:11], v[240:243], v[224:227], v[8:11]
	s_waitcnt lgkmcnt(6)
	v_mfma_f32_16x16x32_bf16 v[4:7], v[128:131], v[220:223], v[4:7]
	s_waitcnt lgkmcnt(4)
	v_mfma_f32_16x16x32_bf16 v[4:7], v[132:135], v[224:227], v[4:7]
	s_waitcnt lgkmcnt(2)
	v_mfma_f32_16x16x32_bf16 v[0:3], v[228:231], v[220:223], v[0:3]
	s_waitcnt lgkmcnt(0)
	v_mfma_f32_16x16x32_bf16 v[0:3], v[232:235], v[224:227], v[0:3]
	v_mov_b32_e32 v129, v171
	s_cmp_lg_u32 s6, 0
	s_cbranch_scc0 .LBB0_2490
	v_mov_b32_e32 v128, v165
	v_mov_b32_e32 v163, v129
	s_branch .LBB0_2492
